# W_out GEMM also uses 288-row tiles (32 extra rows folded into each unit), WO small-tile GEMM removed
# speedup vs baseline: 1.0128x; 1.0128x over previous
; #define PG8_WAIT_V(n) asm volatile("s_waitcnt vmcnt(" #n ")" ::: "memory")
; #define PG8_BAR __builtin_amdgcn_s_barrier()
; template <class Epi, class Sched, bool ALIGN_EPI = false, bool SP2 = false>
; __device__ __forceinline__ void gemm_phase(PG8_LAS unsigned char* lds, const Gemm g, const Sched& S, const Epi& E) {
;     int tid_ = threadIdx.x; asm volatile("" : "+v"(tid_));
;     const int tid = tid_, wid = __builtin_amdgcn_readfirstlane(tid >> 6), lane = tid & 63, wr = wid >> 2, wc = wid & 3, fr = lane & 15, fq = lane >> 4;
;     const int K = g.K, nt = K / BK;
;     unsigned voffA[2], voffB[2];
; #pragma unroll
;     for (int i = 0; i < 2; ++i) { int R, C; stage_rc(tid * 16 + i * 8192, R, C); const int Rb = Epi::PERM ? ((R & ~31) + perm32(R & 31)) : R;
;         voffA[i] = (unsigned)(R * K + C) * 2u; voffB[i] = (unsigned)(Rb * K + C) * 2u; }
;     const size_t kstep = (size_t)(BK * 2);
;     const size_t hstep = (size_t)HALF * K * 2;
;     const size_t tstep = 2 * hstep;
;     const unsigned ldsw = (unsigned)wid * 1024u;
;     const int aoff = lds_byte(wr * 64 + fr, fq * 8), boff = lds_byte(wc * 32 + fr, fq * 8);
;     ...
;     Unit cur, nxt; int ui = 0;
;     if (!S.next(0, cur)) return;
;     f32x4 acc[2][2][4][2];
; #pragma unroll
;     for (int a = 0; a < 2; ++a)
; #pragma unroll
;         for (int b = 0; b < 2; ++b)
; #pragma unroll
;             for (int m = 0; m < 4; ++m)
; #pragma unroll
;                 for (int n = 0; n < 2; ++n) acc[a][b][m][n] = (f32x4){0.f, 0.f, 0.f, 0.f};
;     bf16x8 At[4][2], B0[2][2], B1[2][2];
;     const char* cA = (const char*)g.A + (size_t)cur.pm * tstep; const char* cB = (const char*)g.Bt + (size_t)cur.pn * tstep;
;     S.a_ready(cur);
;     if constexpr (SP2) {
;         PG8_STAGE(PG8_SB(0, 0), cB, voffB); PG8_STAGE(PG8_SB(0, 1), cB + hstep, voffB); PG8_STAGE(PG8_SA(0, 0), cA, voffA); PG8_STAGE(PG8_SA(0, 1), cA + hstep, voffA);
;         if (wr == 1) PG8_BAR;
;         PG8_WAIT_V(2); PG8_BAR;
;         PG8_STAGE(PG8_SB(1, 0), cB + kstep, voffB); PG8_STAGE(PG8_SA(1, 0), cA + kstep, voffA); PG8_STAGE(PG8_SB(1, 1), cB + hstep + kstep, voffB);
;         PG8_WAIT_V(6); PG8_BAR;
;     } else {
;         PG8_STAGE(PG8_SB(0, 0), cB, voffB); PG8_STAGE(PG8_SA(0, 0), cA, voffA); PG8_STAGE(PG8_SB(0, 1), cB + hstep, voffB); PG8_STAGE(PG8_SA(0, 1), cA + hstep, voffA);
;         if (wr == 1) PG8_BAR;
;         PG8_WAIT_V(4); PG8_BAR;
.LBB0_205:
	v_readlane_b32 s0, v251, 17
	v_mov_b32_e32 v14, v216
	v_readlane_b32 s1, v251, 18
	s_andn2_b64 vcc, exec, s[0:1]
	v_readfirstlane_b32 s4, v14
	s_cbranch_vccnz .LBB0_250
	v_lshlrev_b32_e32 v0, 4, v14
	v_add_u32_e32 v1, 0x2000, v0
	v_ashrrev_i32_e32 v2, 31, v1
	v_lshrrev_b32_e32 v2, 22, v2
	v_add_u32_e32 v2, v1, v2
	v_ashrrev_i32_e32 v8, 10, v2
	v_writelane_b32 v255, s52, 27
	v_mul_i32_i24_e32 v2, 0x400, v8
	v_sub_u32_e32 v1, v1, v2
	v_writelane_b32 v255, s53, 28
	v_writelane_b32 v255, s54, 29
	v_lshrrev_b32_e32 v2, 4, v1
	v_writelane_b32 v255, s55, 30
	v_bitop3_b32 v1, v2, v1, 32 bitop3:0x6c
	s_add_u32 s8, s48, 0xef00000
	v_readlane_b32 s0, v255, 19
	v_ashrrev_i32_e32 v2, 31, v1
	s_addc_u32 s9, s49, 0
	v_readlane_b32 s1, v255, 20
	s_mov_b32 s2, s0
	s_ashr_i32 s3, s0, 31
	v_lshrrev_b32_e32 v2, 26, v2
	v_writelane_b32 v255, s0, 19
	s_lshl_b64 s[18:19], s[2:3], 21
	v_add_u32_e32 v2, v1, v2
	v_lshlrev_b32_e32 v3, 3, v8
	v_writelane_b32 v255, s1, 20
	s_add_u32 s0, s48, s18
	v_ashrrev_i32_e32 v9, 6, v2
	v_and_b32_e32 v3, -16, v3
	s_addc_u32 s1, s49, s19
	v_add_u32_e32 v3, v9, v3
	s_add_u32 s12, s0, 0xf00000
	v_and_b32_e32 v4, 3, v9
	s_mov_b32 s0, 0x1fffe0
	v_lshrrev_b32_e32 v5, 2, v3
	v_lshlrev_b32_e32 v6, 1, v3
	v_and_b32_e32 v2, 0xc0, v2
	v_and_or_b32 v4, v3, s0, v4
	v_and_b32_e32 v5, 4, v5
	v_and_b32_e32 v6, 24, v6
	v_sub_u32_e32 v1, v1, v2
	v_or3_b32 v4, v4, v5, v6
	v_lshlrev_b32_e32 v5, 5, v8
	v_ashrrev_i16_sdwa v1, v221, sext(v1) dst_sel:DWORD dst_unused:UNUSED_PAD src0_sel:DWORD src1_sel:BYTE_0
	v_and_b32_e32 v5, 32, v5
	v_bfe_i32 v10, v1, 0, 16
	v_add_lshl_u32 v1, v5, v10, 1
	v_lshl_add_u32 v194, v4, 11, v1
	v_lshl_add_u32 v196, v3, 11, v1
	v_bfe_i32 v1, v14, 27, 1
	v_lshrrev_b32_e32 v1, 22, v1
	v_add_u32_e32 v1, v0, v1
	v_and_b32_e32 v1, 0xfffffc00, v1
	v_sub_u32_e32 v0, v0, v1
	v_lshrrev_b32_e32 v1, 4, v0
	v_ashrrev_i32_e32 v2, 31, v14
	v_bitop3_b32 v0, v1, v0, 32 bitop3:0x6c
	v_lshrrev_b32_e32 v2, 26, v2
	v_ashrrev_i32_e32 v1, 31, v0
	v_add_u32_e32 v2, v14, v2
	v_lshrrev_b32_e32 v1, 26, v1
	v_ashrrev_i32_e32 v12, 6, v2
	v_add_u32_e32 v1, v0, v1
	v_lshlrev_b32_e32 v2, 3, v12
	v_ashrrev_i32_e32 v11, 6, v1
	v_and_b32_e32 v2, -16, v2
	v_add_u32_e32 v2, v11, v2
	v_and_b32_e32 v3, 3, v11
	v_lshrrev_b32_e32 v4, 2, v2
	v_lshlrev_b32_e32 v5, 1, v2
	v_and_b32_e32 v1, 0xc0, v1
	s_addc_u32 s13, s1, 0
	s_ashr_i32 s14, s4, 6
	v_and_or_b32 v3, v2, s0, v3
	v_and_b32_e32 v4, 4, v4
	v_and_b32_e32 v5, 24, v5
	v_sub_u32_e32 v0, v0, v1
	s_ashr_i32 s5, s4, 8
	s_lshl_b32 s44, s14, 10
	v_or3_b32 v3, v3, v4, v5
	v_lshlrev_b32_e32 v4, 5, v12
	v_ashrrev_i16_sdwa v0, v221, sext(v0) dst_sel:DWORD dst_unused:UNUSED_PAD src0_sel:DWORD src1_sel:BYTE_0
	v_readlane_b32 s0, v253, 44
	v_and_b32_e32 v4, 32, v4
	v_bfe_i32 v13, v0, 0, 16
	v_readlane_b32 s1, v253, 45
	s_add_u32 s40, s12, s0
	v_add_lshl_u32 v0, v4, v13, 1
	s_addc_u32 s41, s13, s1
	s_add_i32 s45, s44, 0
	v_lshl_add_u32 v184, v3, 11, v0
	s_add_i32 m0, s45, 0x10000
	v_lshl_add_u32 v198, v2, 11, v0
	global_load_lds_dwordx4 v184, s[40:41]
	s_add_i32 m0, s45, 0x12000
	s_add_u32 s0, s40, 0x40000
	global_load_lds_dwordx4 v194, s[40:41]
	s_addc_u32 s1, s41, 0
	s_add_i32 m0, s45, 0x14000
	v_mov_b32_e32 v195, v185
	global_load_lds_dwordx4 v184, s[0:1]
	s_add_i32 m0, s45, 0x16000
	v_mov_b32_e32 v199, v185
	global_load_lds_dwordx4 v194, s[0:1]
	v_readlane_b32 s0, v254, 5
	s_mul_hi_u32 s1, s0, 0x90000
	s_mul_i32 s0, s0, 0x90000
	s_add_u32 s0, s8, s0
	s_addc_u32 s1, s9, s1
	s_add_i32 s46, s45, 0x2000
	s_mov_b32 m0, s45
	s_add_u32 s2, s0, 0x40000
	global_load_lds_dwordx4 v198, s[0:1]
	s_mov_b32 m0, s46
	s_addc_u32 s3, s1, 0
	s_add_i32 s47, s45, 0x4000
	global_load_lds_dwordx4 v196, s[0:1]
	s_mul_i32 s98, s5, 0x10000
	s_sub_u32 s98, 0x80000, s98
	v_add_u32_e32 v248, s98, v198
	s_and_b32 m0, s44, 0xc00
	s_add_i32 m0, m0, 0x20800
	s_nop 0
	global_load_lds_dwordx4 v248, s[0:1]
	s_mov_b32 m0, s47
	s_add_i32 s48, s45, 0x6000
	global_load_lds_dwordx4 v198, s[2:3]
	s_mov_b32 m0, s48
	v_mov_b32_e32 v197, v185
	global_load_lds_dwordx4 v196, s[2:3]
	s_cmp_eq_u32 s5, 1
	v_lshl_add_u64 v[6:7], s[40:41], 0, v[184:185]
	v_lshl_add_u64 v[4:5], s[40:41], 0, v[194:195]
	v_lshl_add_u64 v[0:1], s[0:1], 0, v[198:199]
	s_cselect_b64 s[2:3], -1, 0
	s_cmp_lg_u32 s5, 1
	v_lshl_add_u64 v[2:3], s[0:1], 0, v[196:197]
	s_cbranch_scc1 .LBB0_208
	s_barrier
.LBB0_208:
	v_readlane_b32 s24, v255, 27
	v_readlane_b32 s26, v255, 29
	s_add_i32 s7, s26, 3
	v_bfe_u32 v15, v14, 4, 2
	s_cmp_lt_u32 s7, 9
	v_and_b32_e32 v16, 15, v14
	v_lshlrev_b32_e32 v18, 4, v15
	v_lshlrev_b32_e32 v14, 2, v14
	s_cselect_b32 s49, s77, s75
	s_cselect_b32 s50, s76, s74
	s_cselect_b32 s7, s79, s57
	s_cselect_b32 s34, s78, s56
	s_and_b32 s24, s14, 3
	v_lshl_or_b32 v227, s5, 6, v16
	v_lshl_or_b32 v16, v16, 6, v18
	s_lshl_b32 s5, s5, 13
	v_and_b32_e32 v14, 32, v14
	s_add_i32 m0, s45, 0x18000
	v_lshl_add_u64 v[6:7], v[6:7], 0, s[96:97]
	v_bitop3_b32 v18, v16, s5, v14 bitop3:0xde
	s_lshl_b32 s5, s24, 12
	s_waitcnt vmcnt(2)
	s_barrier
	global_load_lds_dwordx4 v[6:7], off
	v_lshl_add_u64 v[4:5], v[4:5], 0, s[96:97]
	s_add_i32 m0, s45, 0x1a000
	s_add_i32 s51, s45, 0x8000
	s_add_i32 s52, s45, 0xa000
	global_load_lds_dwordx4 v[4:5], off
	v_lshl_add_u64 v[0:1], v[0:1], 0, s[96:97]
	s_mov_b32 m0, s51
	s_add_u32 s14, s40, 0x40080
	global_load_lds_dwordx4 v[0:1], off
	v_lshl_add_u64 v[0:1], v[2:3], 0, s[96:97]
	s_mov_b32 m0, s52
	s_addc_u32 s15, s41, 0
	global_load_lds_dwordx4 v[0:1], off
	s_add_i32 m0, s45, 0x1c000
	v_lshl_add_u64 v[0:1], s[14:15], 0, v[184:185]
	global_load_lds_dwordx4 v[0:1], off
	v_lshl_add_u64 v[0:1], s[14:15], 0, v[194:195]
	s_add_i32 m0, s45, 0x1e000
	v_bitop3_b32 v228, v16, s5, v14 bitop3:0xde
	global_load_lds_dwordx4 v[0:1], off
	s_add_u32 s98, s0, 0x80
	s_addc_u32 s99, s1, 0
	s_and_b32 m0, s44, 0xc00
	s_add_i32 m0, m0, 0x21800
	s_nop 0
	global_load_lds_dwordx4 v248, s[98:99]
	v_lshlrev_b32_e32 v0, 14, v12
	v_and_b32_e32 v0, 0xffff8000, v0
	s_cmpk_lt_u32 s4, 0x100
	v_readlane_b32 s4, v255, 23
	v_lshl_add_u32 v0, v11, 11, v0
	v_and_b32_e32 v1, 1, v12
	s_cselect_b64 s[20:21], -1, 0
	v_readlane_b32 s5, v255, 24
	s_add_u32 s14, s4, 0x5d00000
	v_lshl_or_b32 v0, v1, 6, v0
	s_addc_u32 s15, s5, 0
	v_lshl_add_u32 v200, v13, 1, v0
	v_lshlrev_b32_e32 v0, 14, v8
	s_add_u32 s16, s4, 0x8600000
	v_and_b32_e32 v0, 0xffff8000, v0
	s_waitcnt vmcnt(7)
	s_addc_u32 s17, s5, 0
	s_lshl_b32 s4, s24, 2
	v_lshl_add_u32 v0, v9, 11, v0
	v_and_b32_e32 v1, 1, v8
	v_lshlrev_b32_e32 v17, 3, v15
	s_add_u32 s54, s16, s4
	v_lshl_or_b32 v0, v1, 6, v0
	v_readlane_b32 s4, v254, 5
	v_lshl_or_b32 v229, s24, 5, v17
	s_mov_b32 s53, 0
	v_cmp_eq_u32_e64 s[36:37], 0, v15
	s_addc_u32 s55, s17, 0
	v_mov_b32_e32 v201, v185
	v_lshl_add_u32 v202, v10, 1, v0
	v_mov_b32_e32 v203, v185
	v_add_u32_e32 v230, 0, v18
	s_lshr_b32 s98, s44, 12
	s_mul_i32 s98, s98, 0x1800
	s_sub_u32 s98, 0x20800, s98
	v_add_u32_e32 v249, s98, v230
	v_readlane_b32 s57, v253, 43
	s_mov_b32 s56, s4
	v_readlane_b32 s25, v255, 28
	v_readlane_b32 s27, v255, 30
	s_barrier
	v_readlane_b32 s5, v254, 6
	s_branch .LBB0_211

; #define PG8_STAGE(bufoff, gbase, voff) do { _Pragma("unroll") for (int _i = 0; _i < 2; ++_i) \
;         __builtin_amdgcn_global_load_lds((const unsigned*)((const char*)(gbase) + (voff)[_i]), (PG8_LAS unsigned*)(lds + (bufoff) + ldsw + _i * 8192), 16, 0, 0); } while (0)
; #define PG8_LDA(dst, b, h) do { _Pragma("unroll") for (int m = 0; m < 4; ++m) _Pragma("unroll") for (int k = 0; k < 2; ++k) dst[m][k] = *(const PG8_LAS bf16x8*)(lds + PG8_SA(b, h) + aoff + m * 2048 + k * 1024); } while (0)
; #define PG8_LDB(dst, b, h) do { _Pragma("unroll") for (int n = 0; n < 2; ++n) _Pragma("unroll") for (int k = 0; k < 2; ++k) dst[n][k] = *(const PG8_LAS bf16x8*)(lds + PG8_SB(b, h) + boff + n * 2048 + k * 1024); } while (0)
; #define PG8_WAIT_V(n) asm volatile("s_waitcnt vmcnt(" #n ")" ::: "memory")
; #define PG8_WAIT_L(n) asm volatile("s_waitcnt lgkmcnt(" #n ")" ::: "memory")
; #define PG8_BAR __builtin_amdgcn_s_barrier()
; template <class Epi, class Sched, bool ALIGN_EPI = false, bool SP2 = false>
; __device__ __forceinline__ void gemm_phase(PG8_LAS unsigned char* lds, const Gemm g, const Sched& S, const Epi& E) {
;     ...
;         const bool has_next = S.next(ui + 1, nxt);
;         const char* nA = has_next ? (const char*)g.A + (size_t)nxt.pm * tstep : cA; const char* nB = has_next ? (const char*)g.Bt + (size_t)nxt.pn * tstep : cB;
;         for (int t = 0; t < nt; t += 2) {
;             const bool last = (t == nt - 2);
;             const char* a1 = cA + (size_t)(t + 1) * kstep;
;             const char* a2 = last ? nA : cA + (size_t)(t + 2) * kstep; const char* b2 = last ? nB : cB + (size_t)(t + 2) * kstep;
;             const char* a3 = a2 + kstep; const char* b3 = b2 + kstep;
;             if (last && has_next) S.a_ready(nxt);
;             if constexpr (SP2) {
;             PG8_LDB(B0, 0, 0); PG8_LDB(B1, 0, 1); PG8_SCHED; PG8_LDA(At, 0, 0); PG8_STAGE(PG8_SA(1, 1), a1 + hstep, voffA);
;             PG8_WAIT_V(8); PG8_WAIT_L(0); PG8_BAR; PG8_MMA(0, 0, At, B0); PG8_MMA(0, 1, At, B1); PG8_BAR; PG8_SCHED;
;     ...
; #pragma unroll
;         for (int a = 0; a < 2; ++a)
; #pragma unroll
;             for (int b = 0; b < 2; ++b)
; #pragma unroll
;                 for (int m = 0; m < 4; ++m)
; #pragma unroll
;                     for (int n = 0; n < 2; ++n) acc[a][b][m][n] = (f32x4){0.f, 0.f, 0.f, 0.f};
;         cur = nxt; cA = nA; cB = nB; ++ui;
.LBB0_217:
	v_readlane_b32 s4, v251, 0
	s_ashr_i32 s27, s26, 31
	s_mul_hi_u32 s5, s26, 0x90000
	s_mul_i32 s4, s26, 0x90000
	s_add_u32 s28, s8, s4
	s_addc_u32 s29, s9, s5
	s_and_b64 s[4:5], s[38:39], exec
	s_cselect_b32 s4, s29, s1
	s_cselect_b32 s5, s28, s0
	s_ashr_i32 s25, s24, 31
	s_lshl_b64 s[30:31], s[24:25], 19
	s_add_u32 s30, s12, s30
	s_addc_u32 s31, s13, s31
	s_and_b64 s[42:43], s[38:39], exec
	s_cselect_b32 s27, s31, s41
	s_cselect_b32 s58, s30, s40
	s_add_u32 s0, s0, 0x40080
	s_addc_u32 s1, s1, 0
	s_add_u32 s59, s40, 0x100
	v_mov_b32_e32 v0, 0
	s_addc_u32 s92, s41, 0
	s_mov_b32 s93, -2
	s_waitcnt lgkmcnt(0)
	v_mov_b32_e32 v1, v0
	v_mov_b32_e32 v2, v0
	v_mov_b32_e32 v3, v0
	v_mov_b32_e32 v4, v0
	v_mov_b32_e32 v5, v0
	v_mov_b32_e32 v6, v0
	v_mov_b32_e32 v7, v0
	v_mov_b32_e32 v16, v0
	v_mov_b32_e32 v17, v0
	v_mov_b32_e32 v18, v0
	v_mov_b32_e32 v19, v0
	v_mov_b32_e32 v20, v0
	v_mov_b32_e32 v21, v0
	v_mov_b32_e32 v22, v0
	v_mov_b32_e32 v23, v0
	v_mov_b32_e32 v32, v0
	v_mov_b32_e32 v33, v0
	v_mov_b32_e32 v34, v0
	v_mov_b32_e32 v35, v0
	v_mov_b32_e32 v36, v0
	v_mov_b32_e32 v37, v0
	v_mov_b32_e32 v38, v0
	v_mov_b32_e32 v39, v0
	v_mov_b32_e32 v48, v0
	v_mov_b32_e32 v49, v0
	v_mov_b32_e32 v50, v0
	v_mov_b32_e32 v51, v0
	v_mov_b32_e32 v52, v0
	v_mov_b32_e32 v53, v0
	v_mov_b32_e32 v54, v0
	v_mov_b32_e32 v55, v0
	v_mov_b32_e32 v8, v0
	v_mov_b32_e32 v9, v0
	v_mov_b32_e32 v10, v0
	v_mov_b32_e32 v11, v0
	v_mov_b32_e32 v12, v0
	v_mov_b32_e32 v13, v0
	v_mov_b32_e32 v14, v0
	v_mov_b32_e32 v15, v0
	v_mov_b32_e32 v24, v0
	v_mov_b32_e32 v25, v0
	v_mov_b32_e32 v26, v0
	v_mov_b32_e32 v27, v0
	v_mov_b32_e32 v28, v0
	v_mov_b32_e32 v29, v0
	v_mov_b32_e32 v30, v0
	v_mov_b32_e32 v31, v0
	v_mov_b32_e32 v40, v0
	v_mov_b32_e32 v41, v0
	v_mov_b32_e32 v42, v0
	v_mov_b32_e32 v43, v0
	v_mov_b32_e32 v44, v0
	v_mov_b32_e32 v45, v0
	v_mov_b32_e32 v46, v0
	v_mov_b32_e32 v47, v0
	v_mov_b32_e32 v56, v0
	v_mov_b32_e32 v57, v0
	v_mov_b32_e32 v58, v0
	v_mov_b32_e32 v59, v0
	v_mov_b32_e32 v60, v0
	v_mov_b32_e32 v61, v0
	v_mov_b32_e32 v62, v0
	v_mov_b32_e32 v63, v0
	v_mov_b32_e32 v64, v0
	v_mov_b32_e32 v65, v0
	v_mov_b32_e32 v66, v0
	v_mov_b32_e32 v67, v0
	v_mov_b32_e32 v68, v0
	v_mov_b32_e32 v69, v0
	v_mov_b32_e32 v70, v0
	v_mov_b32_e32 v71, v0
	v_mov_b32_e32 v80, v0
	v_mov_b32_e32 v81, v0
	v_mov_b32_e32 v82, v0
	v_mov_b32_e32 v83, v0
	v_mov_b32_e32 v84, v0
	v_mov_b32_e32 v85, v0
	v_mov_b32_e32 v86, v0
	v_mov_b32_e32 v87, v0
	v_mov_b32_e32 v96, v0
	v_mov_b32_e32 v97, v0
	v_mov_b32_e32 v98, v0
	v_mov_b32_e32 v99, v0
	v_mov_b32_e32 v100, v0
	v_mov_b32_e32 v101, v0
	v_mov_b32_e32 v102, v0
	v_mov_b32_e32 v103, v0
	v_mov_b32_e32 v112, v0
	v_mov_b32_e32 v113, v0
	v_mov_b32_e32 v114, v0
	v_mov_b32_e32 v115, v0
	v_mov_b32_e32 v116, v0
	v_mov_b32_e32 v117, v0
	v_mov_b32_e32 v118, v0
	v_mov_b32_e32 v119, v0
	v_mov_b32_e32 v72, v0
	v_mov_b32_e32 v73, v0
	v_mov_b32_e32 v74, v0
	v_mov_b32_e32 v75, v0
	v_mov_b32_e32 v76, v0
	v_mov_b32_e32 v77, v0
	v_mov_b32_e32 v78, v0
	v_mov_b32_e32 v79, v0
	v_mov_b32_e32 v88, v0
	v_mov_b32_e32 v89, v0
	v_mov_b32_e32 v90, v0
	v_mov_b32_e32 v91, v0
	v_mov_b32_e32 v92, v0
	v_mov_b32_e32 v93, v0
	v_mov_b32_e32 v94, v0
	v_mov_b32_e32 v95, v0
	v_mov_b32_e32 v104, v0
	v_mov_b32_e32 v105, v0
	v_mov_b32_e32 v106, v0
	v_mov_b32_e32 v107, v0
	v_mov_b32_e32 v108, v0
	v_mov_b32_e32 v109, v0
	v_mov_b32_e32 v110, v0
	v_mov_b32_e32 v111, v0
	v_mov_b32_e32 v120, v0
	v_mov_b32_e32 v121, v0
	v_mov_b32_e32 v122, v0
	v_mov_b32_e32 v123, v0
	v_mov_b32_e32 v124, v0
	v_mov_b32_e32 v125, v0
	v_mov_b32_e32 v126, v0
	v_mov_b32_e32 v127, v0
	v_mov_b32_e32 v236, v0
	v_mov_b32_e32 v237, v0
	v_mov_b32_e32 v238, v0
	v_mov_b32_e32 v239, v0
	v_mov_b32_e32 v240, v0
	v_mov_b32_e32 v241, v0
	v_mov_b32_e32 v242, v0
	v_mov_b32_e32 v243, v0
	v_mov_b32_e32 v244, v0
	v_mov_b32_e32 v245, v0
	v_mov_b32_e32 v246, v0
	v_mov_b32_e32 v247, v0
	v_mov_b32_e32 v200, v0
	v_mov_b32_e32 v201, v0
	v_mov_b32_e32 v202, v0
	v_mov_b32_e32 v203, v0
.LBB0_218:
	s_add_u32 s25, s0, 0xfffc0080
	s_addc_u32 s40, s1, -1
	s_cmp_eq_u32 s93, 12
	s_cselect_b32 s43, s4, s40
	s_cselect_b32 s42, s5, s25
	s_cselect_b32 s41, s27, s92
	s_cselect_b32 s40, s58, s59
	s_add_i32 s94, 0, 0x10000
	s_add_i32 s25, 0, 0x14000
	v_add_u32_e32 v140, s94, v228
	v_add_u32_e32 v156, s25, v228
	ds_read_b128 v[128:131], v140
	ds_read_b128 v[132:135], v140 offset:1024
	ds_read_b128 v[136:139], v140 offset:2048
	ds_read_b128 v[140:143], v140 offset:3072
	ds_read_b128 v[144:147], v156
	ds_read_b128 v[148:151], v156 offset:1024
	ds_read_b128 v[152:155], v156 offset:2048
	ds_read_b128 v[156:159], v156 offset:3072
	s_add_i32 m0, s45, 0xc000
	ds_read_b128 v[160:163], v230
	ds_read_b128 v[164:167], v230 offset:1024
	ds_read_b128 v[168:171], v230 offset:2048
	ds_read_b128 v[172:175], v230 offset:3072
	ds_read_b128 v[176:179], v230 offset:4096
	ds_read_b128 v[180:183], v230 offset:5120
	ds_read_b128 v[204:207], v230 offset:6144
	ds_read_b128 v[208:211], v230 offset:7168
	ds_read_b128 v[212:215], v249
	ds_read_b128 v[232:235], v249 offset:1024
	global_load_lds_dwordx4 v198, s[0:1]
	s_add_i32 m0, s45, 0xe000
	s_nop 0
	global_load_lds_dwordx4 v196, s[0:1]
	s_waitcnt vmcnt(9)
	s_waitcnt lgkmcnt(0)
	s_barrier
; #define PG8_STAGE(bufoff, gbase, voff) do { _Pragma("unroll") for (int _i = 0; _i < 2; ++_i) \
;         __builtin_amdgcn_global_load_lds((const unsigned*)((const char*)(gbase) + (voff)[_i]), (PG8_LAS unsigned*)(lds + (bufoff) + ldsw + _i * 8192), 16, 0, 0); } while (0)
; #define PG8_LDA(dst, b, h) do { _Pragma("unroll") for (int m = 0; m < 4; ++m) _Pragma("unroll") for (int k = 0; k < 2; ++k) dst[m][k] = *(const PG8_LAS bf16x8*)(lds + PG8_SA(b, h) + aoff + m * 2048 + k * 1024); } while (0)
; #define PG8_LDB(dst, b, h) do { _Pragma("unroll") for (int n = 0; n < 2; ++n) _Pragma("unroll") for (int k = 0; k < 2; ++k) dst[n][k] = *(const PG8_LAS bf16x8*)(lds + PG8_SB(b, h) + boff + n * 2048 + k * 1024); } while (0)
; #define PG8_MMA(ai, bj, At, Bt) do { __builtin_amdgcn_s_setprio(1); _Pragma("unroll") for (int m = 0; m < 4; ++m) _Pragma("unroll") for (int n = 0; n < 2; ++n) _Pragma("unroll") for (int k = 0; k < 2; ++k) \
;         acc[ai][bj][m][n] = __builtin_amdgcn_mfma_f32_16x16x32_bf16(Bt[n][k], At[m][k], acc[ai][bj][m][n], 0, 0, 0); __builtin_amdgcn_s_setprio(0); } while (0)
; #define PG8_WAIT_V(n) asm volatile("s_waitcnt vmcnt(" #n ")" ::: "memory")
; #define PG8_WAIT_L(n) asm volatile("s_waitcnt lgkmcnt(" #n ")" ::: "memory")
; #define PG8_BAR __builtin_amdgcn_s_barrier()
; #define PG8_SCHED __builtin_amdgcn_sched_barrier(0)
; template <class Epi, class Sched, bool ALIGN_EPI = false, bool SP2 = false>
; __device__ __forceinline__ void gemm_phase(PG8_LAS unsigned char* lds, const Gemm g, const Sched& S, const Epi& E) {
;     ...
;             PG8_LDB(B0, 0, 0); PG8_LDB(B1, 0, 1); PG8_SCHED; PG8_LDA(At, 0, 0); PG8_STAGE(PG8_SA(1, 1), a1 + hstep, voffA);
;             PG8_WAIT_V(8); PG8_WAIT_L(0); PG8_BAR; PG8_MMA(0, 0, At, B0); PG8_MMA(0, 1, At, B1); PG8_BAR; PG8_SCHED;
;             PG8_LDA(At, 0, 1); PG8_STAGE(PG8_SB(0, 0), b2, voffB); PG8_STAGE(PG8_SB(0, 1), b2 + hstep, voffB); PG8_STAGE(PG8_SA(0, 0), a2, voffA);
	s_setprio 1
	s_waitcnt lgkmcnt(0)
	v_mfma_f32_16x16x32_bf16 v[124:127], v[128:131], v[160:163], v[124:127]
	v_mfma_f32_16x16x32_bf16 v[120:123], v[136:139], v[160:163], v[120:123]
	v_mfma_f32_16x16x32_bf16 v[108:111], v[128:131], v[168:171], v[108:111]
	v_mfma_f32_16x16x32_bf16 v[104:107], v[136:139], v[168:171], v[104:107]
	v_mfma_f32_16x16x32_bf16 v[92:95], v[128:131], v[176:179], v[92:95]
	v_mfma_f32_16x16x32_bf16 v[88:91], v[136:139], v[176:179], v[88:91]
	v_mfma_f32_16x16x32_bf16 v[76:79], v[128:131], v[204:207], v[76:79]
	v_mfma_f32_16x16x32_bf16 v[72:75], v[136:139], v[204:207], v[72:75]
	v_mfma_f32_16x16x32_bf16 v[124:127], v[132:135], v[164:167], v[124:127]
	v_mfma_f32_16x16x32_bf16 v[120:123], v[140:143], v[164:167], v[120:123]
	v_mfma_f32_16x16x32_bf16 v[108:111], v[132:135], v[172:175], v[108:111]
	v_mfma_f32_16x16x32_bf16 v[104:107], v[140:143], v[172:175], v[104:107]
	v_mfma_f32_16x16x32_bf16 v[92:95], v[132:135], v[180:183], v[92:95]
	v_mfma_f32_16x16x32_bf16 v[88:91], v[140:143], v[180:183], v[88:91]
	v_mfma_f32_16x16x32_bf16 v[76:79], v[132:135], v[208:211], v[76:79]
	v_mfma_f32_16x16x32_bf16 v[72:75], v[140:143], v[208:211], v[72:75]
	s_setprio 0
	s_setprio 1
	v_mfma_f32_16x16x32_bf16 v[116:119], v[144:147], v[160:163], v[116:119]
	v_mfma_f32_16x16x32_bf16 v[112:115], v[152:155], v[160:163], v[112:115]
	v_mfma_f32_16x16x32_bf16 v[100:103], v[144:147], v[168:171], v[100:103]
	v_mfma_f32_16x16x32_bf16 v[96:99], v[152:155], v[168:171], v[96:99]
	v_mfma_f32_16x16x32_bf16 v[84:87], v[144:147], v[176:179], v[84:87]
	v_mfma_f32_16x16x32_bf16 v[80:83], v[152:155], v[176:179], v[80:83]
	v_mfma_f32_16x16x32_bf16 v[68:71], v[144:147], v[204:207], v[68:71]
	v_mfma_f32_16x16x32_bf16 v[64:67], v[152:155], v[204:207], v[64:67]
	v_mfma_f32_16x16x32_bf16 v[116:119], v[148:151], v[164:167], v[116:119]
	v_mfma_f32_16x16x32_bf16 v[112:115], v[156:159], v[164:167], v[112:115]
	v_mfma_f32_16x16x32_bf16 v[100:103], v[148:151], v[172:175], v[100:103]
	v_mfma_f32_16x16x32_bf16 v[96:99], v[156:159], v[172:175], v[96:99]
	v_mfma_f32_16x16x32_bf16 v[84:87], v[148:151], v[180:183], v[84:87]
	v_mfma_f32_16x16x32_bf16 v[80:83], v[156:159], v[180:183], v[80:83]
	v_mfma_f32_16x16x32_bf16 v[68:71], v[148:151], v[208:211], v[68:71]
	v_mfma_f32_16x16x32_bf16 v[64:67], v[156:159], v[208:211], v[64:67]
	v_mfma_f32_16x16x32_bf16 v[236:239], v[128:131], v[212:215], v[236:239]
	v_mfma_f32_16x16x32_bf16 v[240:243], v[136:139], v[212:215], v[240:243]
	v_mfma_f32_16x16x32_bf16 v[244:247], v[144:147], v[212:215], v[244:247]
	v_mfma_f32_16x16x32_bf16 v[200:203], v[152:155], v[212:215], v[200:203]
	v_mfma_f32_16x16x32_bf16 v[236:239], v[132:135], v[232:235], v[236:239]
	v_mfma_f32_16x16x32_bf16 v[240:243], v[140:143], v[232:235], v[240:243]
	v_mfma_f32_16x16x32_bf16 v[244:247], v[148:151], v[232:235], v[244:247]
	v_mfma_f32_16x16x32_bf16 v[200:203], v[156:159], v[232:235], v[200:203]
	s_setprio 0
	s_barrier
	s_add_i32 s94, s94, s44
	s_mov_b32 m0, s94
	ds_read_b128 v[160:163], v230 offset:16384
	ds_read_b128 v[164:167], v230 offset:17408
	ds_read_b128 v[168:171], v230 offset:18432
	ds_read_b128 v[172:175], v230 offset:19456
	ds_read_b128 v[176:179], v230 offset:20480
	ds_read_b128 v[180:183], v230 offset:21504
	ds_read_b128 v[204:207], v230 offset:22528
	ds_read_b128 v[208:211], v230 offset:23552
	global_load_lds_dwordx4 v184, s[40:41]
	s_add_i32 m0, s94, 0x2000
	s_add_u32 s98, s40, 0x40000
	s_addc_u32 s99, s41, 0
	s_add_i32 s25, s25, s44
	global_load_lds_dwordx4 v194, s[40:41]
	s_mov_b32 m0, s25
	s_nop 0
	global_load_lds_dwordx4 v184, s[98:99]
	s_add_i32 m0, s25, 0x2000
	s_nop 0
	global_load_lds_dwordx4 v194, s[98:99]
	s_mov_b32 m0, s45
	s_nop 0
	global_load_lds_dwordx4 v198, s[42:43]
	s_mov_b32 m0, s46
	s_nop 0
	global_load_lds_dwordx4 v196, s[42:43]
	s_and_b32 m0, s44, 0xc00
	s_add_i32 m0, m0, 0x20800
	s_nop 0
	global_load_lds_dwordx4 v248, s[42:43]
	s_waitcnt vmcnt(9)
	s_waitcnt lgkmcnt(0)
	s_barrier
	s_setprio 1
	s_waitcnt lgkmcnt(0)
	v_mfma_f32_16x16x32_bf16 v[60:63], v[128:131], v[160:163], v[60:63]
	v_mfma_f32_16x16x32_bf16 v[56:59], v[136:139], v[160:163], v[56:59]
	v_mfma_f32_16x16x32_bf16 v[44:47], v[128:131], v[168:171], v[44:47]
	v_mfma_f32_16x16x32_bf16 v[40:43], v[136:139], v[168:171], v[40:43]
	v_mfma_f32_16x16x32_bf16 v[28:31], v[128:131], v[176:179], v[28:31]
	v_mfma_f32_16x16x32_bf16 v[24:27], v[136:139], v[176:179], v[24:27]
	v_mfma_f32_16x16x32_bf16 v[12:15], v[128:131], v[204:207], v[12:15]
	v_mfma_f32_16x16x32_bf16 v[8:11], v[136:139], v[204:207], v[8:11]
	v_mfma_f32_16x16x32_bf16 v[60:63], v[132:135], v[164:167], v[60:63]
	v_mfma_f32_16x16x32_bf16 v[56:59], v[140:143], v[164:167], v[56:59]
	v_mfma_f32_16x16x32_bf16 v[44:47], v[132:135], v[172:175], v[44:47]
	v_mfma_f32_16x16x32_bf16 v[40:43], v[140:143], v[172:175], v[40:43]
	v_mfma_f32_16x16x32_bf16 v[28:31], v[132:135], v[180:183], v[28:31]
	v_mfma_f32_16x16x32_bf16 v[24:27], v[140:143], v[180:183], v[24:27]
	v_mfma_f32_16x16x32_bf16 v[12:15], v[132:135], v[208:211], v[12:15]
	v_mfma_f32_16x16x32_bf16 v[8:11], v[140:143], v[208:211], v[8:11]
	s_setprio 0
	s_setprio 1
	v_mfma_f32_16x16x32_bf16 v[52:55], v[144:147], v[160:163], v[52:55]
	v_mfma_f32_16x16x32_bf16 v[48:51], v[152:155], v[160:163], v[48:51]
	v_mfma_f32_16x16x32_bf16 v[36:39], v[144:147], v[168:171], v[36:39]
	v_mfma_f32_16x16x32_bf16 v[32:35], v[152:155], v[168:171], v[32:35]
	v_mfma_f32_16x16x32_bf16 v[20:23], v[144:147], v[176:179], v[20:23]
	v_mfma_f32_16x16x32_bf16 v[16:19], v[152:155], v[176:179], v[16:19]
	v_mfma_f32_16x16x32_bf16 v[4:7], v[144:147], v[204:207], v[4:7]
	v_mfma_f32_16x16x32_bf16 v[0:3], v[152:155], v[204:207], v[0:3]
	v_mfma_f32_16x16x32_bf16 v[52:55], v[148:151], v[164:167], v[52:55]
	v_mfma_f32_16x16x32_bf16 v[48:51], v[156:159], v[164:167], v[48:51]
	v_mfma_f32_16x16x32_bf16 v[36:39], v[148:151], v[172:175], v[36:39]
	v_mfma_f32_16x16x32_bf16 v[32:35], v[156:159], v[172:175], v[32:35]
	v_mfma_f32_16x16x32_bf16 v[20:23], v[148:151], v[180:183], v[20:23]
	v_mfma_f32_16x16x32_bf16 v[16:19], v[156:159], v[180:183], v[16:19]
	v_mfma_f32_16x16x32_bf16 v[4:7], v[148:151], v[208:211], v[4:7]
	v_mfma_f32_16x16x32_bf16 v[0:3], v[156:159], v[208:211], v[0:3]
	s_setprio 0
	s_barrier
; #define PG8_STAGE(bufoff, gbase, voff) do { _Pragma("unroll") for (int _i = 0; _i < 2; ++_i) \
;         __builtin_amdgcn_global_load_lds((const unsigned*)((const char*)(gbase) + (voff)[_i]), (PG8_LAS unsigned*)(lds + (bufoff) + ldsw + _i * 8192), 16, 0, 0); } while (0)
; #define PG8_LDA(dst, b, h) do { _Pragma("unroll") for (int m = 0; m < 4; ++m) _Pragma("unroll") for (int k = 0; k < 2; ++k) dst[m][k] = *(const PG8_LAS bf16x8*)(lds + PG8_SA(b, h) + aoff + m * 2048 + k * 1024); } while (0)
; #define PG8_LDB(dst, b, h) do { _Pragma("unroll") for (int n = 0; n < 2; ++n) _Pragma("unroll") for (int k = 0; k < 2; ++k) dst[n][k] = *(const PG8_LAS bf16x8*)(lds + PG8_SB(b, h) + boff + n * 2048 + k * 1024); } while (0)
; #define PG8_MMA(ai, bj, At, Bt) do { __builtin_amdgcn_s_setprio(1); _Pragma("unroll") for (int m = 0; m < 4; ++m) _Pragma("unroll") for (int n = 0; n < 2; ++n) _Pragma("unroll") for (int k = 0; k < 2; ++k) \
;         acc[ai][bj][m][n] = __builtin_amdgcn_mfma_f32_16x16x32_bf16(Bt[n][k], At[m][k], acc[ai][bj][m][n], 0, 0, 0); __builtin_amdgcn_s_setprio(0); } while (0)
; #define PG8_WAIT_V(n) asm volatile("s_waitcnt vmcnt(" #n ")" ::: "memory")
; #define PG8_WAIT_L(n) asm volatile("s_waitcnt lgkmcnt(" #n ")" ::: "memory")
; #define PG8_BAR __builtin_amdgcn_s_barrier()
; #define PG8_SCHED __builtin_amdgcn_sched_barrier(0)
; template <class Epi, class Sched, bool ALIGN_EPI = false, bool SP2 = false>
; __device__ __forceinline__ void gemm_phase(PG8_LAS unsigned char* lds, const Gemm g, const Sched& S, const Epi& E) {
;     ...
;             PG8_LDA(At, 0, 1); PG8_STAGE(PG8_SB(0, 0), b2, voffB); PG8_STAGE(PG8_SB(0, 1), b2 + hstep, voffB); PG8_STAGE(PG8_SA(0, 0), a2, voffA);
;             PG8_WAIT_V(8); PG8_WAIT_L(0); PG8_BAR; PG8_MMA(1, 0, At, B0); PG8_MMA(1, 1, At, B1); PG8_BAR; PG8_SCHED;
;             PG8_LDB(B0, 1, 0); PG8_LDB(B1, 1, 1); PG8_SCHED; PG8_LDA(At, 1, 0); PG8_STAGE(PG8_SA(0, 1), a2 + hstep, voffA);
;             PG8_WAIT_V(8); PG8_WAIT_L(0); PG8_BAR; PG8_MMA(0, 0, At, B0); PG8_MMA(0, 1, At, B1); PG8_BAR; PG8_SCHED;
;             PG8_LDA(At, 1, 1); PG8_STAGE(PG8_SB(1, 0), b3, voffB); PG8_STAGE(PG8_SB(1, 1), b3 + hstep, voffB); PG8_STAGE(PG8_SA(1, 0), a3, voffA);
	s_add_i32 s25, 0, 0x18000
	s_add_i32 s94, 0, 0x1c000
	v_add_u32_e32 v140, s25, v228
	v_add_u32_e32 v156, s94, v228
	ds_read_b128 v[128:131], v140
	ds_read_b128 v[132:135], v140 offset:1024
	ds_read_b128 v[136:139], v140 offset:2048
	ds_read_b128 v[140:143], v140 offset:3072
	ds_read_b128 v[144:147], v156
	ds_read_b128 v[148:151], v156 offset:1024
	ds_read_b128 v[152:155], v156 offset:2048
	ds_read_b128 v[156:159], v156 offset:3072
	s_add_u32 s98, s42, 0x40000
	s_addc_u32 s99, s43, 0
	s_mov_b32 m0, s47
	ds_read_b128 v[160:163], v230 offset:32768
	ds_read_b128 v[164:167], v230 offset:33792
	ds_read_b128 v[168:171], v230 offset:34816
	ds_read_b128 v[172:175], v230 offset:35840
	ds_read_b128 v[176:179], v230 offset:36864
	ds_read_b128 v[180:183], v230 offset:37888
	ds_read_b128 v[204:207], v230 offset:38912
	ds_read_b128 v[208:211], v230 offset:39936
	ds_read_b128 v[212:215], v249 offset:4096
	ds_read_b128 v[232:235], v249 offset:5120
	global_load_lds_dwordx4 v198, s[98:99]
	s_mov_b32 m0, s48
	s_nop 0
	global_load_lds_dwordx4 v196, s[98:99]
	s_waitcnt vmcnt(9)
	s_waitcnt lgkmcnt(0)
	s_barrier
	s_setprio 1
	s_waitcnt lgkmcnt(0)
	v_mfma_f32_16x16x32_bf16 v[124:127], v[128:131], v[160:163], v[124:127]
	v_mfma_f32_16x16x32_bf16 v[120:123], v[136:139], v[160:163], v[120:123]
	v_mfma_f32_16x16x32_bf16 v[108:111], v[128:131], v[168:171], v[108:111]
	v_mfma_f32_16x16x32_bf16 v[104:107], v[136:139], v[168:171], v[104:107]
	v_mfma_f32_16x16x32_bf16 v[92:95], v[128:131], v[176:179], v[92:95]
	v_mfma_f32_16x16x32_bf16 v[88:91], v[136:139], v[176:179], v[88:91]
	v_mfma_f32_16x16x32_bf16 v[76:79], v[128:131], v[204:207], v[76:79]
	v_mfma_f32_16x16x32_bf16 v[72:75], v[136:139], v[204:207], v[72:75]
	v_mfma_f32_16x16x32_bf16 v[124:127], v[132:135], v[164:167], v[124:127]
	v_mfma_f32_16x16x32_bf16 v[120:123], v[140:143], v[164:167], v[120:123]
	v_mfma_f32_16x16x32_bf16 v[108:111], v[132:135], v[172:175], v[108:111]
	v_mfma_f32_16x16x32_bf16 v[104:107], v[140:143], v[172:175], v[104:107]
	v_mfma_f32_16x16x32_bf16 v[92:95], v[132:135], v[180:183], v[92:95]
	v_mfma_f32_16x16x32_bf16 v[88:91], v[140:143], v[180:183], v[88:91]
	v_mfma_f32_16x16x32_bf16 v[76:79], v[132:135], v[208:211], v[76:79]
	v_mfma_f32_16x16x32_bf16 v[72:75], v[140:143], v[208:211], v[72:75]
	s_setprio 0
	s_setprio 1
	v_mfma_f32_16x16x32_bf16 v[116:119], v[144:147], v[160:163], v[116:119]
	v_mfma_f32_16x16x32_bf16 v[112:115], v[152:155], v[160:163], v[112:115]
	v_mfma_f32_16x16x32_bf16 v[100:103], v[144:147], v[168:171], v[100:103]
	v_mfma_f32_16x16x32_bf16 v[96:99], v[152:155], v[168:171], v[96:99]
	v_mfma_f32_16x16x32_bf16 v[84:87], v[144:147], v[176:179], v[84:87]
	v_mfma_f32_16x16x32_bf16 v[80:83], v[152:155], v[176:179], v[80:83]
	v_mfma_f32_16x16x32_bf16 v[68:71], v[144:147], v[204:207], v[68:71]
	v_mfma_f32_16x16x32_bf16 v[64:67], v[152:155], v[204:207], v[64:67]
	v_mfma_f32_16x16x32_bf16 v[116:119], v[148:151], v[164:167], v[116:119]
	v_mfma_f32_16x16x32_bf16 v[112:115], v[156:159], v[164:167], v[112:115]
	v_mfma_f32_16x16x32_bf16 v[100:103], v[148:151], v[172:175], v[100:103]
	v_mfma_f32_16x16x32_bf16 v[96:99], v[156:159], v[172:175], v[96:99]
	v_mfma_f32_16x16x32_bf16 v[84:87], v[148:151], v[180:183], v[84:87]
	v_mfma_f32_16x16x32_bf16 v[80:83], v[156:159], v[180:183], v[80:83]
	v_mfma_f32_16x16x32_bf16 v[68:71], v[148:151], v[208:211], v[68:71]
	v_mfma_f32_16x16x32_bf16 v[64:67], v[156:159], v[208:211], v[64:67]
	v_mfma_f32_16x16x32_bf16 v[236:239], v[128:131], v[212:215], v[236:239]
	v_mfma_f32_16x16x32_bf16 v[240:243], v[136:139], v[212:215], v[240:243]
	v_mfma_f32_16x16x32_bf16 v[244:247], v[144:147], v[212:215], v[244:247]
	v_mfma_f32_16x16x32_bf16 v[200:203], v[152:155], v[212:215], v[200:203]
	v_mfma_f32_16x16x32_bf16 v[236:239], v[132:135], v[232:235], v[236:239]
	v_mfma_f32_16x16x32_bf16 v[240:243], v[140:143], v[232:235], v[240:243]
	v_mfma_f32_16x16x32_bf16 v[244:247], v[148:151], v[232:235], v[244:247]
	v_mfma_f32_16x16x32_bf16 v[200:203], v[156:159], v[232:235], v[200:203]
	s_setprio 0
	s_barrier
	s_add_i32 s25, s25, s44
	s_add_u32 s98, s40, 0x80
	s_addc_u32 s99, s41, 0
	s_mov_b32 m0, s25
	ds_read_b128 v[160:163], v230 offset:49152
	ds_read_b128 v[164:167], v230 offset:50176
	ds_read_b128 v[168:171], v230 offset:51200
	ds_read_b128 v[172:175], v230 offset:52224
	ds_read_b128 v[176:179], v230 offset:53248
	ds_read_b128 v[180:183], v230 offset:54272
	ds_read_b128 v[204:207], v230 offset:55296
	ds_read_b128 v[208:211], v230 offset:56320
	global_load_lds_dwordx4 v184, s[98:99]
	s_add_i32 m0, s25, 0x2000
	s_add_u32 s100, s40, 0x40080
	s_addc_u32 s101, s41, 0
	s_add_i32 s94, s94, s44
	global_load_lds_dwordx4 v194, s[98:99]
	s_mov_b32 m0, s94
	s_add_u32 s98, s42, 0x80
	s_addc_u32 s99, s43, 0
	global_load_lds_dwordx4 v184, s[100:101]
	s_add_i32 m0, s94, 0x2000
	s_nop 0
	global_load_lds_dwordx4 v194, s[100:101]
	s_mov_b32 m0, s51
	s_nop 0
	global_load_lds_dwordx4 v198, s[98:99]
	s_mov_b32 m0, s52
	s_nop 0
	global_load_lds_dwordx4 v196, s[98:99]
	s_and_b32 m0, s44, 0xc00
	s_add_i32 m0, m0, 0x21800
	s_nop 0
	global_load_lds_dwordx4 v248, s[98:99]
	s_waitcnt vmcnt(9)
	s_waitcnt lgkmcnt(0)
	s_barrier
; __device__ __forceinline__ float quad_sum(float s) { s += __shfl_xor(s, 16); s += __shfl_xor(s, 32); return s; }
; __device__ __forceinline__ float sq4(const f32x4 a) { return (a[0] * a[0] + a[1] * a[1]) + (a[2] * a[2] + a[3] * a[3]); }
; #define PG8_WAIT_V(n) asm volatile("s_waitcnt vmcnt(" #n ")" ::: "memory")
;     __device__ __forceinline__ void operator()(const f32x4 (&acc)[2][2][4][2], const Unit& u, int wr, int wc, int fr, int fq) const {
;         bf16_t* AB = (bf16_t*)(ws + WS_AB); float* PS = (float*)(ws + WS_PS);
;         const int col0 = u.pn * BM + wc * 32 + 8 * fq;
; #pragma unroll
;         for (int ai = 0; ai < 2; ++ai) {
;             f32x4 bv[4][2][2];
; #pragma unroll
;             for (int m = 0; m < 4; ++m) {
;                 const int row = u.pm * BM + ai * HALF + wr * 64 + m * 16 + fr;
;                 const float* bp = (u.pm < 64) ? base_p + (size_t)row * 1024 : base_s + (size_t)(row - E_MP) * 1024;
; #pragma unroll
;                 for (int bj = 0; bj < 2; ++bj) { bv[m][bj][0] = *(const f32x4*)(bp + col0 + bj * HALF); bv[m][bj][1] = *(const f32x4*)(bp + col0 + bj * HALF + 4); }
;             }
; #pragma unroll
;             for (int m = 0; m < 4; ++m) {
;                 const int row = u.pm * BM + ai * HALF + wr * 64 + m * 16 + fr;
;                 float ss = 0.f;
; #pragma unroll
;                 for (int bj = 0; bj < 2; ++bj) {
;                     const int c = col0 + bj * HALF;
;                     const f32x4 y0 = bv[m][bj][0] + acc[ai][bj][m][0], y1 = bv[m][bj][1] + acc[ai][bj][m][1];
;                     float* d = out + (size_t)row * 1024 + c; *(f32x4*)d = y0; *(f32x4*)(d + 4) = y1;
;                     *(u32x4*)(AB + (size_t)row * 1024 + c) = pack8(y0, y1);
;                     ss += sq4(y0) + sq4(y1);
;                 }
;                 ss = quad_sum(ss);
;                 if (fq == 0) PS[(size_t)row * 16 + u.pn * 4 + wc] = ss;
;             }
; template <class Epi, class Sched, bool ALIGN_EPI = false, bool SP2 = false>
; __device__ __forceinline__ void gemm_phase(PG8_LAS unsigned char* lds, const Gemm g, const Sched& S, const Epi& E) {
;     ...
;             PG8_LDA(At, 1, 1); PG8_STAGE(PG8_SB(1, 0), b3, voffB); PG8_STAGE(PG8_SB(1, 1), b3 + hstep, voffB); PG8_STAGE(PG8_SA(1, 0), a3, voffA);
;             PG8_WAIT_V(8); PG8_WAIT_L(0); PG8_BAR; PG8_MMA(1, 0, At, B0); PG8_MMA(1, 1, At, B1); PG8_BAR; PG8_SCHED;
	s_setprio 1
	s_waitcnt lgkmcnt(0)
	v_mfma_f32_16x16x32_bf16 v[60:63], v[128:131], v[160:163], v[60:63]
	v_mfma_f32_16x16x32_bf16 v[56:59], v[136:139], v[160:163], v[56:59]
	v_mfma_f32_16x16x32_bf16 v[44:47], v[128:131], v[168:171], v[44:47]
	v_mfma_f32_16x16x32_bf16 v[40:43], v[136:139], v[168:171], v[40:43]
	v_mfma_f32_16x16x32_bf16 v[28:31], v[128:131], v[176:179], v[28:31]
	v_mfma_f32_16x16x32_bf16 v[24:27], v[136:139], v[176:179], v[24:27]
	v_mfma_f32_16x16x32_bf16 v[12:15], v[128:131], v[204:207], v[12:15]
	v_mfma_f32_16x16x32_bf16 v[8:11], v[136:139], v[204:207], v[8:11]
	v_mfma_f32_16x16x32_bf16 v[60:63], v[132:135], v[164:167], v[60:63]
	v_mfma_f32_16x16x32_bf16 v[56:59], v[140:143], v[164:167], v[56:59]
	v_mfma_f32_16x16x32_bf16 v[44:47], v[132:135], v[172:175], v[44:47]
	v_mfma_f32_16x16x32_bf16 v[40:43], v[140:143], v[172:175], v[40:43]
	v_mfma_f32_16x16x32_bf16 v[28:31], v[132:135], v[180:183], v[28:31]
	v_mfma_f32_16x16x32_bf16 v[24:27], v[140:143], v[180:183], v[24:27]
	v_mfma_f32_16x16x32_bf16 v[12:15], v[132:135], v[208:211], v[12:15]
	v_mfma_f32_16x16x32_bf16 v[8:11], v[140:143], v[208:211], v[8:11]
	s_setprio 0
	s_setprio 1
	v_mfma_f32_16x16x32_bf16 v[52:55], v[144:147], v[160:163], v[52:55]
	v_mfma_f32_16x16x32_bf16 v[48:51], v[152:155], v[160:163], v[48:51]
	v_mfma_f32_16x16x32_bf16 v[36:39], v[144:147], v[168:171], v[36:39]
	v_mfma_f32_16x16x32_bf16 v[32:35], v[152:155], v[168:171], v[32:35]
	v_mfma_f32_16x16x32_bf16 v[20:23], v[144:147], v[176:179], v[20:23]
	v_mfma_f32_16x16x32_bf16 v[16:19], v[152:155], v[176:179], v[16:19]
	v_mfma_f32_16x16x32_bf16 v[4:7], v[144:147], v[204:207], v[4:7]
	v_mfma_f32_16x16x32_bf16 v[0:3], v[152:155], v[204:207], v[0:3]
	v_mfma_f32_16x16x32_bf16 v[52:55], v[148:151], v[164:167], v[52:55]
	v_mfma_f32_16x16x32_bf16 v[48:51], v[156:159], v[164:167], v[48:51]
	v_mfma_f32_16x16x32_bf16 v[36:39], v[148:151], v[172:175], v[36:39]
	v_mfma_f32_16x16x32_bf16 v[32:35], v[156:159], v[172:175], v[32:35]
	v_mfma_f32_16x16x32_bf16 v[20:23], v[148:151], v[180:183], v[20:23]
	v_mfma_f32_16x16x32_bf16 v[16:19], v[156:159], v[180:183], v[16:19]
	v_mfma_f32_16x16x32_bf16 v[4:7], v[148:151], v[208:211], v[4:7]
	v_mfma_f32_16x16x32_bf16 v[0:3], v[156:159], v[208:211], v[0:3]
	s_setprio 0
	s_barrier
	s_add_i32 s93, s93, 2
	s_add_u32 s0, s0, 0x100
	s_addc_u32 s1, s1, 0
	s_add_u32 s59, s59, 0x100
	s_addc_u32 s92, s92, 0
	s_cmp_gt_u32 s93, 13
	s_cbranch_scc0 .LBB0_218
	s_and_b64 vcc, exec, s[20:21]
	s_cbranch_vccz .LBB0_221
	s_barrier
.LBB0_221:
	s_mul_i32 s98, s56, 0x120
	v_and_b32_e32 v128, 15, v227
	v_lshrrev_b32_e32 v129, 6, v227
	v_lshl_add_u32 v128, v129, 4, v128
	v_add_u32_e32 v128, s98, v128
	v_add_u32_e32 v128, 0x100, v128
	v_mov_b32_e32 v129, 0
	v_lshl_or_b32 v130, s57, 8, v229
	v_mov_b32_e32 v131, 0
	s_cmp_lt_i32 s56, 56
	s_cselect_b32 s98, s50, s34
	s_cselect_b32 s99, s49, s7
	s_cselect_b32 s100, 0, 0x4000
	v_subrev_u32_e32 v166, s100, v128
	v_mov_b32_e32 v167, 0
	v_lshlrev_b64 v[166:167], 12, v[166:167]
	v_lshl_add_u64 v[166:167], s[98:99], 0, v[166:167]
	v_lshl_add_u64 v[166:167], v[130:131], 2, v[166:167]
	global_load_dwordx4 v[136:139], v[166:167], off
	global_load_dwordx4 v[140:143], v[166:167], off offset:16
	global_load_dwordx4 v[144:147], v[166:167], off offset:512
	global_load_dwordx4 v[148:151], v[166:167], off offset:528
	v_lshlrev_b64 v[132:133], 12, v[128:129]
	v_lshl_add_u64 v[132:133], s[74:75], 0, v[132:133]
	v_lshl_add_u64 v[132:133], v[130:131], 2, v[132:133]
	v_lshlrev_b64 v[134:135], 11, v[128:129]
	v_lshl_add_u64 v[134:135], s[14:15], 0, v[134:135]
	v_lshl_add_u64 v[134:135], v[130:131], 1, v[134:135]
	s_lshl_b32 s98, s57, 4
	s_add_u32 s98, s54, s98
	s_addc_u32 s99, s55, 0
	v_lshlrev_b64 v[164:165], 6, v[128:129]
	v_lshl_add_u64 v[164:165], s[98:99], 0, v[164:165]
	v_xor_b32_e32 v162, 16, v222
	v_lshlrev_b32_e32 v162, 2, v162
	v_xor_b32_e32 v163, 32, v222
	v_lshlrev_b32_e32 v163, 2, v163
	s_waitcnt vmcnt(0)
	v_pk_add_f32 v[136:137], v[236:237], v[136:137]
	v_pk_add_f32 v[138:139], v[238:239], v[138:139]
	v_pk_add_f32 v[140:141], v[240:241], v[140:141]
	v_pk_add_f32 v[142:143], v[242:243], v[142:143]
	v_pk_add_f32 v[144:145], v[244:245], v[144:145]
	v_pk_add_f32 v[146:147], v[246:247], v[146:147]
	v_pk_add_f32 v[148:149], v[200:201], v[148:149]
	v_pk_add_f32 v[150:151], v[202:203], v[150:151]
	global_store_dwordx4 v[132:133], v[136:139], off
	global_store_dwordx4 v[132:133], v[140:143], off offset:16
	global_store_dwordx4 v[132:133], v[144:147], off offset:512
	global_store_dwordx4 v[132:133], v[148:151], off offset:528
	v_cvt_pk_bf16_f32 v152, v136, v137
	v_cvt_pk_bf16_f32 v153, v138, v139
	v_cvt_pk_bf16_f32 v154, v140, v141
	v_cvt_pk_bf16_f32 v155, v142, v143
	v_cvt_pk_bf16_f32 v156, v144, v145
	v_cvt_pk_bf16_f32 v157, v146, v147
	v_cvt_pk_bf16_f32 v158, v148, v149
	v_cvt_pk_bf16_f32 v159, v150, v151
	global_store_dwordx4 v[134:135], v[152:155], off
	global_store_dwordx4 v[134:135], v[156:159], off offset:256
	v_mul_f32_e32 v160, v136, v136
	v_fmac_f32_e32 v160, v137, v137
	v_fmac_f32_e32 v160, v138, v138
	v_fmac_f32_e32 v160, v139, v139
	v_fmac_f32_e32 v160, v140, v140
	v_fmac_f32_e32 v160, v141, v141
	v_fmac_f32_e32 v160, v142, v142
	v_fmac_f32_e32 v160, v143, v143
	v_fmac_f32_e32 v160, v144, v144
	v_fmac_f32_e32 v160, v145, v145
	v_fmac_f32_e32 v160, v146, v146
	v_fmac_f32_e32 v160, v147, v147
	v_fmac_f32_e32 v160, v148, v148
	v_fmac_f32_e32 v160, v149, v149
	v_fmac_f32_e32 v160, v150, v150
	v_fmac_f32_e32 v160, v151, v151
	ds_bpermute_b32 v161, v162, v160
	s_waitcnt lgkmcnt(0)
	v_add_f32_e32 v160, v160, v161
	ds_bpermute_b32 v161, v163, v160
	s_waitcnt lgkmcnt(0)
; __device__ __forceinline__ float quad_sum(float s) { s += __shfl_xor(s, 16); s += __shfl_xor(s, 32); return s; }
; __device__ __forceinline__ float sq4(const f32x4 a) { return (a[0] * a[0] + a[1] * a[1]) + (a[2] * a[2] + a[3] * a[3]); }
; __device__ __forceinline__ u32x4 pack8(const f32x4 a, const f32x4 b) { u32x4 w; w.x = cvt_pk_bf16(a[0], a[1]); w.y = cvt_pk_bf16(a[2], a[3]); w.z = cvt_pk_bf16(b[0], b[1]); w.w = cvt_pk_bf16(b[2], b[3]); return w; }
;     __device__ __forceinline__ void operator()(const f32x4 (&acc)[2][2][4][2], const Unit& u, int wr, int wc, int fr, int fq) const {
;         bf16_t* AB = (bf16_t*)(ws + WS_AB); float* PS = (float*)(ws + WS_PS);
;         const int col0 = u.pn * BM + wc * 32 + 8 * fq;
; #pragma unroll
;         for (int ai = 0; ai < 2; ++ai) {
;             f32x4 bv[4][2][2];
; #pragma unroll
;             for (int m = 0; m < 4; ++m) {
;                 const int row = u.pm * BM + ai * HALF + wr * 64 + m * 16 + fr;
;                 const float* bp = (u.pm < 64) ? base_p + (size_t)row * 1024 : base_s + (size_t)(row - E_MP) * 1024;
; #pragma unroll
;                 for (int bj = 0; bj < 2; ++bj) { bv[m][bj][0] = *(const f32x4*)(bp + col0 + bj * HALF); bv[m][bj][1] = *(const f32x4*)(bp + col0 + bj * HALF + 4); }
;             }
; #pragma unroll
;             for (int m = 0; m < 4; ++m) {
;                 const int row = u.pm * BM + ai * HALF + wr * 64 + m * 16 + fr;
;                 float ss = 0.f;
; #pragma unroll
;                 for (int bj = 0; bj < 2; ++bj) {
;                     const int c = col0 + bj * HALF;
;                     const f32x4 y0 = bv[m][bj][0] + acc[ai][bj][m][0], y1 = bv[m][bj][1] + acc[ai][bj][m][1];
;                     float* d = out + (size_t)row * 1024 + c; *(f32x4*)d = y0; *(f32x4*)(d + 4) = y1;
;                     *(u32x4*)(AB + (size_t)row * 1024 + c) = pack8(y0, y1);
;                     ss += sq4(y0) + sq4(y1);
;                 }
;                 ss = quad_sum(ss);
;                 if (fq == 0) PS[(size_t)row * 16 + u.pn * 4 + wc] = ss;
;             }
	v_add_f32_e32 v160, v160, v161
	s_and_saveexec_b64 s[98:99], s[36:37]
	global_store_dword v[164:165], v160, off
	s_or_b64 exec, exec, s[98:99]
	s_lshl_b32 s0, s57, 2
	s_ashr_i32 s1, s0, 31
	s_lshl_b64 s[0:1], s[0:1], 2
	s_add_u32 s40, s54, s0
	s_addc_u32 s41, s55, s1
	s_mul_i32 s98, s56, 0x120
	v_add_u32_e32 v208, s98, v227
	s_cmp_lt_i32 s56, 57
	s_cselect_b64 vcc, -1, 0
	v_add_u32_e32 v128, 0xffffc000, v208
	v_cndmask_b32_e32 v128, v128, v208, vcc
	v_lshl_or_b32 v204, s57, 8, v229
	s_and_b64 s[0:1], vcc, exec
	v_ashrrev_i32_e32 v129, 31, v128
	v_ashrrev_i32_e32 v205, 31, v204
	s_cselect_b32 s43, s49, s7
	s_cselect_b32 s42, s50, s34
	v_lshlrev_b64 v[128:129], 12, v[128:129]
	v_lshl_add_u64 v[128:129], s[42:43], 0, v[128:129]
	v_lshlrev_b64 v[206:207], 2, v[204:205]
	v_lshl_add_u64 v[128:129], v[128:129], 0, v[206:207]
	global_load_dwordx4 v[232:235], v[128:129], off offset:16
	global_load_dwordx4 v[236:239], v[128:129], off
	global_load_dwordx4 v[176:179], v[128:129], off offset:528
	global_load_dwordx4 v[180:183], v[128:129], off offset:512
	v_add_u32_e32 v214, 16, v208
	v_add_u32_e32 v128, 0xffffc010, v208
	v_cndmask_b32_e32 v128, v128, v214, vcc
	v_ashrrev_i32_e32 v129, 31, v128
	v_lshlrev_b64 v[128:129], 12, v[128:129]
	v_lshl_add_u64 v[128:129], s[42:43], 0, v[128:129]
	v_lshl_add_u64 v[128:129], v[128:129], 0, v[206:207]
	global_load_dwordx4 v[168:171], v[128:129], off offset:16
	global_load_dwordx4 v[172:175], v[128:129], off
	global_load_dwordx4 v[160:163], v[128:129], off offset:528
	global_load_dwordx4 v[164:167], v[128:129], off offset:512
	v_add_u32_e32 v212, 32, v208
	v_add_u32_e32 v128, 0xffffc020, v208
	v_cndmask_b32_e32 v128, v128, v212, vcc
	v_ashrrev_i32_e32 v129, 31, v128
	v_lshlrev_b64 v[128:129], 12, v[128:129]
	v_lshl_add_u64 v[128:129], s[42:43], 0, v[128:129]
	v_lshl_add_u64 v[128:129], v[128:129], 0, v[206:207]
	global_load_dwordx4 v[152:155], v[128:129], off offset:16
	global_load_dwordx4 v[156:159], v[128:129], off
	global_load_dwordx4 v[136:139], v[128:129], off offset:528
	global_load_dwordx4 v[140:143], v[128:129], off offset:512
	v_add_u32_e32 v210, 48, v208
	v_add_u32_e32 v128, 0xffffc030, v208
	v_cndmask_b32_e32 v128, v128, v210, vcc
	v_ashrrev_i32_e32 v129, 31, v128
	v_lshlrev_b64 v[128:129], 12, v[128:129]
	v_lshl_add_u64 v[128:129], s[42:43], 0, v[128:129]
	v_lshl_add_u64 v[132:133], v[128:129], 0, v[206:207]
	global_load_dwordx4 v[144:147], v[132:133], off offset:16
	global_load_dwordx4 v[148:151], v[132:133], off
	global_load_dwordx4 v[128:131], v[132:133], off offset:528
	s_nop 0
	global_load_dwordx4 v[132:135], v[132:133], off offset:512
	v_ashrrev_i32_e32 v209, 31, v208
	v_lshlrev_b64 v[224:225], 11, v[208:209]
	v_lshl_add_u64 v[224:225], s[14:15], 0, v[224:225]
	v_lshl_add_u64 v[224:225], v[204:205], 1, v[224:225]
	s_waitcnt vmcnt(0)
	v_pk_add_f32 v[120:121], v[120:121], v[232:233]
	v_lshlrev_b64 v[232:233], 12, v[208:209]
	v_lshl_add_u64 v[232:233], s[74:75], 0, v[232:233]
	v_pk_add_f32 v[126:127], v[126:127], v[238:239]
	v_pk_add_f32 v[124:125], v[124:125], v[236:237]
	v_lshl_add_u64 v[236:237], v[232:233], 0, v[206:207]
	v_pk_add_f32 v[122:123], v[122:123], v[234:235]
	global_store_dwordx4 v[236:237], v[124:127], off
	global_store_dwordx4 v[236:237], v[120:123], off offset:16
	v_cvt_pk_bf16_f32 v232, v124, v125
	v_cvt_pk_bf16_f32 v233, v126, v127
	v_cvt_pk_bf16_f32 v234, v120, v121
	v_pk_add_f32 v[118:119], v[118:119], v[182:183]
	v_mul_f32_e32 v125, v125, v125
	v_mul_f32_e32 v121, v121, v121
	v_fmac_f32_e32 v125, v124, v124
	v_mul_f32_e32 v124, v127, v127
	v_fmac_f32_e32 v121, v120, v120
	v_mul_f32_e32 v120, v123, v123
	v_fmac_f32_e32 v124, v126, v126
	v_fmac_f32_e32 v120, v122, v122
	v_add_f32_e32 v124, v125, v124
	v_add_f32_e32 v120, v121, v120
	v_pk_add_f32 v[116:117], v[116:117], v[180:181]
	v_pk_add_f32 v[112:113], v[112:113], v[176:177]
	v_cvt_pk_bf16_f32 v235, v122, v123
	global_store_dwordx4 v[224:225], v[232:235], off
	v_add_f32_e32 v124, v124, v120
	v_pk_add_f32 v[114:115], v[114:115], v[178:179]
	global_store_dwordx4 v[236:237], v[116:119], off offset:512
	global_store_dwordx4 v[236:237], v[112:115], off offset:528
	v_cvt_pk_bf16_f32 v120, v116, v117
	v_cvt_pk_bf16_f32 v121, v118, v119
	v_cvt_pk_bf16_f32 v122, v112, v113
	v_cvt_pk_bf16_f32 v123, v114, v115
	s_nop 0
	v_mul_f32_e32 v117, v117, v117
	v_mul_f32_e32 v113, v113, v113
	v_fmac_f32_e32 v113, v112, v112
	v_mul_f32_e32 v112, v115, v115
	v_fmac_f32_e32 v117, v116, v116
	v_mul_f32_e32 v116, v119, v119
	v_fmac_f32_e32 v112, v114, v114
	v_and_b32_e32 v114, 64, v222
	v_fmac_f32_e32 v116, v118, v118
	v_add_f32_e32 v112, v113, v112
	v_xor_b32_e32 v113, 16, v222
	v_add_u32_e32 v114, 64, v114
	v_add_f32_e32 v116, v117, v116
	v_cmp_lt_i32_e64 s[0:1], v113, v114
	v_add_f32_e32 v112, v116, v112
	v_add_f32_e32 v112, v124, v112
	v_cndmask_b32_e64 v113, v222, v113, s[0:1]
	v_lshlrev_b32_e32 v176, 2, v113
	ds_bpermute_b32 v113, v176, v112
	global_store_dwordx4 v[224:225], v[120:123], off offset:256
	s_waitcnt lgkmcnt(0)
	v_add_f32_e32 v112, v112, v113
	v_xor_b32_e32 v113, 32, v222
	v_cmp_lt_i32_e64 s[0:1], v113, v114
	s_nop 1
	v_cndmask_b32_e64 v113, v222, v113, s[0:1]
	v_lshlrev_b32_e32 v177, 2, v113
	ds_bpermute_b32 v113, v177, v112
	s_and_saveexec_b64 s[0:1], s[36:37]
	v_readlane_b32 s58, v255, 9
	v_readlane_b32 s59, v255, 10
	v_readlane_b32 s92, v255, 11
	v_readlane_b32 s93, v255, 16
	s_cbranch_execz .LBB0_223
	v_lshlrev_b64 v[114:115], 6, v[208:209]
	v_lshl_add_u64 v[114:115], s[40:41], 0, v[114:115]
	s_waitcnt lgkmcnt(0)
	v_add_f32_e32 v112, v112, v113
	global_store_dword v[114:115], v112, off

; __global__ void __launch_bounds__(NWAVES * 64, 2) hymba_fwd(Args args) {
;     ...
;                 for (int st = (int)blockIdx.x; st < 256; st += G)
;                     small_gemm_res(lds, (const bf16*)(ws + WS_MIX), (const bf16*)(ws + WS_WOUT) + (size_t)l * D * D, D, l == 0 ? args.in[1] : args.out + O_YS, args.out, (bf16*)(ws + WS_AB), (float*)(ws + WS_PS), (st & 7) * 4 + ((st >> 3) & 3), st >> 5, tid);
.LBB0_240:
	v_readlane_b32 s0, v254, 23
	v_readlane_b32 s2, v255, 17
	v_readlane_b32 s3, v255, 18
	s_add_u32 s0, s0, s2
	v_readlane_b32 s1, v254, 24
	s_addc_u32 s1, s1, s3
	s_add_u32 s2, s2, s18
	s_waitcnt vmcnt(0)
	s_addc_u32 s3, s3, s19
	v_readlane_b32 s4, v254, 27
	s_add_u32 s2, s4, s2
	v_readlane_b32 s4, v254, 28
	v_readlane_b32 s52, v255, 27
	v_readlane_b32 s48, v255, 23
	s_addc_u32 s3, s4, s3
	v_readlane_b32 s24, v254, 25
	v_readlane_b32 s26, v251, 0
	v_readlane_b32 s53, v255, 28
	v_readlane_b32 s54, v255, 29
	v_readlane_b32 s55, v255, 30
	v_readlane_b32 s56, v255, 14
	v_readlane_b32 s57, v255, 15
	v_readlane_b32 s49, v255, 24
	s_barrier
	s_branch .LBB0_250
.LBB0_250:
	s_mov_b64 s[0:1], 0
